# GEMM K-loop: first two counted waits after an epilogue with atomics relaxed by the epilogue's own 24 stores/atomics (phases 7, 8, 10)
# baseline (speedup 1.0000x reference)
.LBB0_1769:
	s_mov_b32 s98, 0
	v_readlane_b32 s4, v244, 47
	v_readlane_b32 s5, v244, 48
	v_readlane_b32 s6, v244, 49
	v_readlane_b32 s7, v244, 50
	s_cmp_lt_i32 s4, 8
	v_readlane_b32 s4, v244, 0
	v_readlane_b32 s5, v244, 1
	v_readlane_b32 s6, v244, 2
	v_readlane_b32 s7, v244, 3
	v_readlane_b32 s8, v244, 4
	v_readlane_b32 s9, v244, 5
	v_readlane_b32 s10, v244, 6
	v_readlane_b32 s11, v244, 7
	s_mov_b64 s[4:5], s[8:9]
	s_mov_b64 s[6:7], s[10:11]
	s_cselect_b64 s[2:3], -1, 0
	s_add_u32 s6, s6, 0x1fa00000
	s_addc_u32 s7, s7, 0
	s_and_b64 s[4:5], s[2:3], s[0:1]
	s_andn2_b64 vcc, exec, s[4:5]
	s_cbranch_vccnz .LBB0_1804
	v_readlane_b32 s2, v244, 51
	s_cmpk_lt_i32 s2, 0x300
	s_cselect_b64 s[0:1], -1, 0
	s_cmpk_gt_i32 s2, 0x2ff
	v_readfirstlane_b32 s2, v182
	s_cbranch_scc1 .LBB0_1772
	v_readlane_b32 s9, v244, 51
	s_ashr_i32 s3, s9, 31
	s_lshr_b32 s3, s3, 29
	s_add_i32 s3, s9, s3
	s_ashr_i32 s8, s3, 3
	s_and_b32 s3, s3, -8
	s_sub_i32 s3, s9, s3
	s_cmp_lt_i32 s3, 0
	s_movk_i32 s9, 0x61
	s_cselect_b32 s9, s9, 0x60
	s_mul_i32 s3, s3, s9
	s_add_i32 s3, s3, s8
	s_ashr_i32 s8, s3, 31
	s_lshr_b32 s8, s8, 27
	s_add_i32 s8, s3, s8
	s_ashr_i32 s9, s8, 5
	s_and_b32 s8, s8, 0xffe0
	s_sub_i32 s3, s3, s8
	s_bfe_i32 s8, s3, 0x80000
	s_bfe_u32 s8, s8, 0x3000c
	s_add_i32 s8, s3, s8
	s_bfe_i32 s10, s8, 0x80000
	s_and_b32 s8, s8, 0xf8
	s_sub_i32 s3, s3, s8
	s_lshl_b32 s9, s9, 3
	s_sext_i32_i16 s10, s10
	s_sext_i32_i8 s3, s3
	s_add_i32 s28, s9, s3
	s_ashr_i32 s26, s10, 3

.LBB0_1781:
	s_cmp_eq_u32 s56, 6
	s_cbranch_scc0 .Lp7_skip_rescale
	v_readlane_b32 s98, v244, 6
	v_readlane_b32 s99, v244, 7
	v_lshl_add_u32 v232, s28, 8, v145
	s_add_u32 s98, s98, 0x1fb20000
	s_addc_u32 s99, s99, 0
	v_lshlrev_b32_e32 v232, 2, v232
	s_add_u32 s100, s98, 0x30000
	s_addc_u32 s101, s99, 0
	global_load_dword v233, v232, s[98:99] offset:0
	global_load_dword v234, v232, s[98:99] offset:64
	global_load_dword v235, v232, s[98:99] offset:128
	global_load_dword v236, v232, s[98:99] offset:192
	global_load_dword v237, v232, s[98:99] offset:512
	global_load_dword v238, v232, s[98:99] offset:576
	global_load_dword v239, v232, s[98:99] offset:640
	global_load_dword v240, v232, s[98:99] offset:704
	global_load_dword v241, v232, s[100:101] offset:0
	global_load_dword v242, v232, s[100:101] offset:64
	global_load_dword v243, v232, s[100:101] offset:128
	global_load_dword v245, v232, s[100:101] offset:192
	global_load_dword v246, v232, s[100:101] offset:512
	global_load_dword v247, v232, s[100:101] offset:576
	global_load_dword v248, v232, s[100:101] offset:640
	global_load_dword v249, v232, s[100:101] offset:704
	v_mov_b32_e32 v250, 0x358637bd
	s_waitcnt vmcnt(0)
	v_fmamk_f32 v233, v233, 0x3b000000, v250
	v_fmamk_f32 v234, v234, 0x3b000000, v250
	v_fmamk_f32 v235, v235, 0x3b000000, v250
	v_fmamk_f32 v236, v236, 0x3b000000, v250
	v_fmamk_f32 v237, v237, 0x3b000000, v250
	v_fmamk_f32 v238, v238, 0x3b000000, v250
	v_fmamk_f32 v239, v239, 0x3b000000, v250
	v_fmamk_f32 v240, v240, 0x3b000000, v250
	v_fmamk_f32 v241, v241, 0x3b000000, v250
	v_fmamk_f32 v242, v242, 0x3b000000, v250
	v_fmamk_f32 v243, v243, 0x3b000000, v250
	v_fmamk_f32 v245, v245, 0x3b000000, v250
	v_fmamk_f32 v246, v246, 0x3b000000, v250
	v_fmamk_f32 v247, v247, 0x3b000000, v250
	v_fmamk_f32 v248, v248, 0x3b000000, v250
	v_fmamk_f32 v249, v249, 0x3b000000, v250
	v_rcp_f32_e32 v233, v233
	v_rcp_f32_e32 v234, v234
	v_rcp_f32_e32 v235, v235
	v_rcp_f32_e32 v236, v236
	v_rcp_f32_e32 v237, v237
	v_rcp_f32_e32 v238, v238
	v_rcp_f32_e32 v239, v239
	v_rcp_f32_e32 v240, v240
	s_nop 0
	v_mul_f32_e32 v233, v233, v241
	v_mul_f32_e32 v234, v234, v242
	v_mul_f32_e32 v235, v235, v243
	v_mul_f32_e32 v236, v236, v245
	v_mul_f32_e32 v237, v237, v246
	v_mul_f32_e32 v238, v238, v247
	v_mul_f32_e32 v239, v239, v248
	v_mul_f32_e32 v240, v240, v249
	v_sqrt_f32_e32 v233, v233
	v_sqrt_f32_e32 v234, v234
	v_sqrt_f32_e32 v235, v235
	v_sqrt_f32_e32 v236, v236
	v_sqrt_f32_e32 v237, v237
	v_sqrt_f32_e32 v238, v238
	v_sqrt_f32_e32 v239, v239
	v_sqrt_f32_e32 v240, v240
	v_rsq_f32_e32 v241, v241
	v_rsq_f32_e32 v242, v242
	v_rsq_f32_e32 v243, v243
	v_rsq_f32_e32 v245, v245
	v_rsq_f32_e32 v246, v246
	v_rsq_f32_e32 v247, v247
	v_rsq_f32_e32 v248, v248
	v_rsq_f32_e32 v249, v249
	s_nop 0
	v_mul_f32_e32 v112, v112, v233
	v_mul_f32_e32 v113, v113, v233
	v_mul_f32_e32 v114, v114, v233
	v_mul_f32_e32 v115, v115, v233
	v_mul_f32_e32 v116, v116, v233
	v_mul_f32_e32 v117, v117, v233
	v_mul_f32_e32 v118, v118, v233
	v_mul_f32_e32 v119, v119, v233
	v_mul_f32_e32 v120, v120, v233
	v_mul_f32_e32 v121, v121, v233
	v_mul_f32_e32 v122, v122, v233
	v_mul_f32_e32 v123, v123, v233
	v_mul_f32_e32 v124, v124, v233
	v_mul_f32_e32 v125, v125, v233
	v_mul_f32_e32 v126, v126, v233
	v_mul_f32_e32 v127, v127, v233
	v_mul_f32_e32 v96, v96, v234
	v_mul_f32_e32 v97, v97, v234
	v_mul_f32_e32 v98, v98, v234
	v_mul_f32_e32 v99, v99, v234
	v_mul_f32_e32 v100, v100, v234
	v_mul_f32_e32 v101, v101, v234
	v_mul_f32_e32 v102, v102, v234
	v_mul_f32_e32 v103, v103, v234
	v_mul_f32_e32 v104, v104, v234
	v_mul_f32_e32 v105, v105, v234
	v_mul_f32_e32 v106, v106, v234
	v_mul_f32_e32 v107, v107, v234
	v_mul_f32_e32 v108, v108, v234
	v_mul_f32_e32 v109, v109, v234
	v_mul_f32_e32 v110, v110, v234
	v_mul_f32_e32 v111, v111, v234
	v_mul_f32_e32 v80, v80, v235
	v_mul_f32_e32 v81, v81, v235
	v_mul_f32_e32 v82, v82, v235
	v_mul_f32_e32 v83, v83, v235
	v_mul_f32_e32 v84, v84, v235
	v_mul_f32_e32 v85, v85, v235
	v_mul_f32_e32 v86, v86, v235
	v_mul_f32_e32 v87, v87, v235
	v_mul_f32_e32 v88, v88, v235
	v_mul_f32_e32 v89, v89, v235
	v_mul_f32_e32 v90, v90, v235
	v_mul_f32_e32 v91, v91, v235
	v_mul_f32_e32 v92, v92, v235
	v_mul_f32_e32 v93, v93, v235
	v_mul_f32_e32 v94, v94, v235
	v_mul_f32_e32 v95, v95, v235
	v_mul_f32_e32 v64, v64, v236
	v_mul_f32_e32 v65, v65, v236
	v_mul_f32_e32 v66, v66, v236
	v_mul_f32_e32 v67, v67, v236
	v_mul_f32_e32 v68, v68, v236
	v_mul_f32_e32 v69, v69, v236
	v_mul_f32_e32 v70, v70, v236
	v_mul_f32_e32 v71, v71, v236
	v_mul_f32_e32 v72, v72, v236
	v_mul_f32_e32 v73, v73, v236
	v_mul_f32_e32 v74, v74, v236
	v_mul_f32_e32 v75, v75, v236
	v_mul_f32_e32 v76, v76, v236
	v_mul_f32_e32 v77, v77, v236
	v_mul_f32_e32 v78, v78, v236
	v_mul_f32_e32 v79, v79, v236
	v_mul_f32_e32 v48, v48, v237
	v_mul_f32_e32 v49, v49, v237
	v_mul_f32_e32 v50, v50, v237
	v_mul_f32_e32 v51, v51, v237
	v_mul_f32_e32 v52, v52, v237
	v_mul_f32_e32 v53, v53, v237
	v_mul_f32_e32 v54, v54, v237
	v_mul_f32_e32 v55, v55, v237
	v_mul_f32_e32 v56, v56, v237
	v_mul_f32_e32 v57, v57, v237
	v_mul_f32_e32 v58, v58, v237
	v_mul_f32_e32 v59, v59, v237
	v_mul_f32_e32 v60, v60, v237
	v_mul_f32_e32 v61, v61, v237
	v_mul_f32_e32 v62, v62, v237
	v_mul_f32_e32 v63, v63, v237
	v_mul_f32_e32 v32, v32, v238
	v_mul_f32_e32 v33, v33, v238
	v_mul_f32_e32 v34, v34, v238
	v_mul_f32_e32 v35, v35, v238
	v_mul_f32_e32 v36, v36, v238
	v_mul_f32_e32 v37, v37, v238
	v_mul_f32_e32 v38, v38, v238
	v_mul_f32_e32 v39, v39, v238
	v_mul_f32_e32 v40, v40, v238
	v_mul_f32_e32 v41, v41, v238
	v_mul_f32_e32 v42, v42, v238
	v_mul_f32_e32 v43, v43, v238
	v_mul_f32_e32 v44, v44, v238
	v_mul_f32_e32 v45, v45, v238
	v_mul_f32_e32 v46, v46, v238
	v_mul_f32_e32 v47, v47, v238
	v_mul_f32_e32 v16, v16, v239
	v_mul_f32_e32 v17, v17, v239
	v_mul_f32_e32 v18, v18, v239
	v_mul_f32_e32 v19, v19, v239
	v_mul_f32_e32 v20, v20, v239
	v_mul_f32_e32 v21, v21, v239
	v_mul_f32_e32 v22, v22, v239
	v_mul_f32_e32 v23, v23, v239
	v_mul_f32_e32 v24, v24, v239
	v_mul_f32_e32 v25, v25, v239
	v_mul_f32_e32 v26, v26, v239
	v_mul_f32_e32 v27, v27, v239
	v_mul_f32_e32 v28, v28, v239
	v_mul_f32_e32 v29, v29, v239
	v_mul_f32_e32 v30, v30, v239
	v_mul_f32_e32 v31, v31, v239
	v_mul_f32_e32 v0, v0, v240
	v_mul_f32_e32 v1, v1, v240
	v_mul_f32_e32 v2, v2, v240
	v_mul_f32_e32 v3, v3, v240
	v_mul_f32_e32 v4, v4, v240
	v_mul_f32_e32 v5, v5, v240
	v_mul_f32_e32 v6, v6, v240
	v_mul_f32_e32 v7, v7, v240
	v_mul_f32_e32 v8, v8, v240
	v_mul_f32_e32 v9, v9, v240
	v_mul_f32_e32 v10, v10, v240
	v_mul_f32_e32 v11, v11, v240
	v_mul_f32_e32 v12, v12, v240
	v_mul_f32_e32 v13, v13, v240
	v_mul_f32_e32 v14, v14, v240
	v_mul_f32_e32 v15, v15, v240
	s_mov_b32 s98, 0
.Lp7_skip_rescale:
	ds_read_b128 v[128:131], v184
	ds_read_b128 v[132:135], v184 offset:1024
	ds_read_b128 v[136:139], v184 offset:2048
	ds_read_b128 v[140:143], v184 offset:3072
	ds_read_b128 v[166:169], v185
	ds_read_b128 v[170:173], v185 offset:1024
	ds_read_b128 v[174:177], v185 offset:2048
	ds_read_b128 v[188:191], v185 offset:3072
	s_add_u32 s34, s30, 0xfffc0080
	s_addc_u32 s35, s31, -1
	s_cmp_eq_u32 s56, 12
	s_cselect_b32 s37, s21, s35
	s_cselect_b32 s36, s27, s34
	s_cselect_b32 s35, s19, s55
	s_cselect_b32 s34, s29, s54
	v_lshl_add_u64 v[178:179], s[30:31], 0, v[158:159]
	s_add_i32 m0, s42, 0xc000
	ds_read_b128 v[192:195], v186
	ds_read_b128 v[196:199], v186 offset:1024
	ds_read_b128 v[200:203], v186 offset:2048
	ds_read_b128 v[204:207], v186 offset:3072
	ds_read_b128 v[208:211], v186 offset:4096
	ds_read_b128 v[212:215], v186 offset:5120
	ds_read_b128 v[216:219], v186 offset:6144
	ds_read_b128 v[220:223], v186 offset:7168
	global_load_lds_dwordx4 v[178:179], off
	v_lshl_add_u64 v[178:179], s[30:31], 0, v[160:161]
	s_add_i32 m0, s42, 0xe000
	s_nop 0
	global_load_lds_dwordx4 v[178:179], off
	s_cmp_lg_u32 s98, 0
	s_cbranch_scc1 .Lrelax7_r1
	s_waitcnt vmcnt(8)
	s_branch .Lrelax7_d1
.Lrelax7_r1:
	s_waitcnt vmcnt(32)
.Lrelax7_d1:
	s_waitcnt lgkmcnt(0)
	s_barrier
	s_setprio 1
	s_waitcnt lgkmcnt(0)
	v_mfma_f32_16x16x32_bf16 v[124:127], v[128:131], v[192:195], v[124:127]
	v_mfma_f32_16x16x32_bf16 v[120:123], v[136:139], v[192:195], v[120:123]
	v_mfma_f32_16x16x32_bf16 v[108:111], v[128:131], v[200:203], v[108:111]
	v_mfma_f32_16x16x32_bf16 v[104:107], v[136:139], v[200:203], v[104:107]
	v_mfma_f32_16x16x32_bf16 v[92:95], v[128:131], v[208:211], v[92:95]
	v_mfma_f32_16x16x32_bf16 v[88:91], v[136:139], v[208:211], v[88:91]
	v_mfma_f32_16x16x32_bf16 v[76:79], v[128:131], v[216:219], v[76:79]
	v_mfma_f32_16x16x32_bf16 v[72:75], v[136:139], v[216:219], v[72:75]
	v_mfma_f32_16x16x32_bf16 v[124:127], v[132:135], v[196:199], v[124:127]
	v_mfma_f32_16x16x32_bf16 v[120:123], v[140:143], v[196:199], v[120:123]
	v_mfma_f32_16x16x32_bf16 v[108:111], v[132:135], v[204:207], v[108:111]
	v_mfma_f32_16x16x32_bf16 v[104:107], v[140:143], v[204:207], v[104:107]
	v_mfma_f32_16x16x32_bf16 v[92:95], v[132:135], v[212:215], v[92:95]
	v_mfma_f32_16x16x32_bf16 v[88:91], v[140:143], v[212:215], v[88:91]
	v_mfma_f32_16x16x32_bf16 v[76:79], v[132:135], v[220:223], v[76:79]
	v_mfma_f32_16x16x32_bf16 v[72:75], v[140:143], v[220:223], v[72:75]
	s_setprio 0
	s_setprio 1
	v_mfma_f32_16x16x32_bf16 v[116:119], v[166:169], v[192:195], v[116:119]
	v_mfma_f32_16x16x32_bf16 v[112:115], v[174:177], v[192:195], v[112:115]
	v_mfma_f32_16x16x32_bf16 v[100:103], v[166:169], v[200:203], v[100:103]
	v_mfma_f32_16x16x32_bf16 v[96:99], v[174:177], v[200:203], v[96:99]
	v_mfma_f32_16x16x32_bf16 v[84:87], v[166:169], v[208:211], v[84:87]
	v_mfma_f32_16x16x32_bf16 v[80:83], v[174:177], v[208:211], v[80:83]
	v_mfma_f32_16x16x32_bf16 v[68:71], v[166:169], v[216:219], v[68:71]
	v_mfma_f32_16x16x32_bf16 v[64:67], v[174:177], v[216:219], v[64:67]
	v_mfma_f32_16x16x32_bf16 v[116:119], v[170:173], v[196:199], v[116:119]
	v_mfma_f32_16x16x32_bf16 v[112:115], v[188:191], v[196:199], v[112:115]
	v_mfma_f32_16x16x32_bf16 v[100:103], v[170:173], v[204:207], v[100:103]
	v_mfma_f32_16x16x32_bf16 v[96:99], v[188:191], v[204:207], v[96:99]
	v_mfma_f32_16x16x32_bf16 v[84:87], v[170:173], v[212:215], v[84:87]
	v_mfma_f32_16x16x32_bf16 v[80:83], v[188:191], v[212:215], v[80:83]
	v_mfma_f32_16x16x32_bf16 v[68:71], v[170:173], v[220:223], v[68:71]
	v_mfma_f32_16x16x32_bf16 v[64:67], v[188:191], v[220:223], v[64:67]
	s_setprio 0
	s_barrier
	s_add_i32 s57, s52, s41
	v_lshl_add_u64 v[178:179], s[34:35], 0, v[148:149]
	s_mov_b32 m0, s57
	ds_read_b128 v[192:195], v186 offset:16384
	ds_read_b128 v[196:199], v186 offset:17408
	ds_read_b128 v[200:203], v186 offset:18432
	ds_read_b128 v[204:207], v186 offset:19456
	ds_read_b128 v[208:211], v186 offset:20480
	ds_read_b128 v[212:215], v186 offset:21504
	ds_read_b128 v[216:219], v186 offset:22528
	ds_read_b128 v[220:223], v186 offset:23552
	global_load_lds_dwordx4 v[178:179], off
	s_add_i32 m0, s57, 0x2000
	s_add_u32 s58, s34, 0x40000
	v_lshl_add_u64 v[224:225], s[34:35], 0, v[152:153]
	s_addc_u32 s59, s35, 0
	s_add_i32 s57, s53, s41
	global_load_lds_dwordx4 v[224:225], off
	v_lshl_add_u64 v[226:227], s[58:59], 0, v[148:149]
	s_mov_b32 m0, s57
	v_lshl_add_u64 v[228:229], s[36:37], 0, v[150:151]
	global_load_lds_dwordx4 v[226:227], off
	v_lshl_add_u64 v[226:227], s[58:59], 0, v[152:153]
	s_add_i32 m0, s57, 0x2000
	s_nop 0
	global_load_lds_dwordx4 v[226:227], off
	v_lshl_add_u64 v[226:227], s[36:37], 0, v[146:147]
	s_mov_b32 m0, s42
	s_nop 0
	global_load_lds_dwordx4 v[226:227], off
	s_mov_b32 m0, s43
	s_nop 0
	global_load_lds_dwordx4 v[228:229], off
	s_cmp_lg_u32 s98, 0
	s_cbranch_scc1 .Lrelax7_r2
	s_waitcnt vmcnt(8)
	s_branch .Lrelax7_d2

.Lrelax7_d2:
	s_mov_b32 s98, 0
	s_waitcnt lgkmcnt(0)
	s_barrier
	s_setprio 1
	s_waitcnt lgkmcnt(0)
	v_mfma_f32_16x16x32_bf16 v[60:63], v[128:131], v[192:195], v[60:63]
	v_mfma_f32_16x16x32_bf16 v[56:59], v[136:139], v[192:195], v[56:59]
	v_mfma_f32_16x16x32_bf16 v[44:47], v[128:131], v[200:203], v[44:47]
	v_mfma_f32_16x16x32_bf16 v[40:43], v[136:139], v[200:203], v[40:43]
	v_mfma_f32_16x16x32_bf16 v[28:31], v[128:131], v[208:211], v[28:31]
	v_mfma_f32_16x16x32_bf16 v[24:27], v[136:139], v[208:211], v[24:27]
	v_mfma_f32_16x16x32_bf16 v[12:15], v[128:131], v[216:219], v[12:15]
	v_mfma_f32_16x16x32_bf16 v[8:11], v[136:139], v[216:219], v[8:11]
	v_mfma_f32_16x16x32_bf16 v[60:63], v[132:135], v[196:199], v[60:63]
	v_mfma_f32_16x16x32_bf16 v[56:59], v[140:143], v[196:199], v[56:59]
	v_mfma_f32_16x16x32_bf16 v[44:47], v[132:135], v[204:207], v[44:47]
	v_mfma_f32_16x16x32_bf16 v[40:43], v[140:143], v[204:207], v[40:43]
	v_mfma_f32_16x16x32_bf16 v[28:31], v[132:135], v[212:215], v[28:31]
	v_mfma_f32_16x16x32_bf16 v[24:27], v[140:143], v[212:215], v[24:27]
	v_mfma_f32_16x16x32_bf16 v[12:15], v[132:135], v[220:223], v[12:15]
	v_mfma_f32_16x16x32_bf16 v[8:11], v[140:143], v[220:223], v[8:11]
	s_setprio 0
	s_setprio 1
	v_mfma_f32_16x16x32_bf16 v[52:55], v[166:169], v[192:195], v[52:55]
	v_mfma_f32_16x16x32_bf16 v[48:51], v[174:177], v[192:195], v[48:51]
	v_mfma_f32_16x16x32_bf16 v[36:39], v[166:169], v[200:203], v[36:39]
	v_mfma_f32_16x16x32_bf16 v[32:35], v[174:177], v[200:203], v[32:35]
	v_mfma_f32_16x16x32_bf16 v[20:23], v[166:169], v[208:211], v[20:23]
	v_mfma_f32_16x16x32_bf16 v[16:19], v[174:177], v[208:211], v[16:19]
	v_mfma_f32_16x16x32_bf16 v[4:7], v[166:169], v[216:219], v[4:7]
	v_mfma_f32_16x16x32_bf16 v[0:3], v[174:177], v[216:219], v[0:3]
	v_mfma_f32_16x16x32_bf16 v[52:55], v[170:173], v[196:199], v[52:55]
	v_mfma_f32_16x16x32_bf16 v[48:51], v[188:191], v[196:199], v[48:51]
	v_mfma_f32_16x16x32_bf16 v[36:39], v[170:173], v[204:207], v[36:39]
	v_mfma_f32_16x16x32_bf16 v[32:35], v[188:191], v[204:207], v[32:35]
	v_mfma_f32_16x16x32_bf16 v[20:23], v[170:173], v[212:215], v[20:23]
	v_mfma_f32_16x16x32_bf16 v[16:19], v[188:191], v[212:215], v[16:19]
	v_mfma_f32_16x16x32_bf16 v[4:7], v[170:173], v[220:223], v[4:7]
	v_mfma_f32_16x16x32_bf16 v[0:3], v[188:191], v[220:223], v[0:3]
	s_setprio 0
	s_barrier
	s_add_i32 s57, 0, 0x18000
	s_add_i32 s58, 0, 0x1c000
	v_add_u32_e32 v140, s57, v183
	v_add_u32_e32 v188, s58, v183
	ds_read_b128 v[128:131], v140
	ds_read_b128 v[132:135], v140 offset:1024
	ds_read_b128 v[136:139], v140 offset:2048
	ds_read_b128 v[140:143], v140 offset:3072
	ds_read_b128 v[166:169], v188
	ds_read_b128 v[170:173], v188 offset:1024
	ds_read_b128 v[174:177], v188 offset:2048
	ds_read_b128 v[188:191], v188 offset:3072
	s_add_u32 s36, s36, 0x40000
	s_addc_u32 s37, s37, 0
	s_mov_b32 m0, s44
	v_lshl_add_u64 v[230:231], s[36:37], 0, v[146:147]
	ds_read_b128 v[192:195], v186 offset:32768
	ds_read_b128 v[196:199], v186 offset:33792
	ds_read_b128 v[200:203], v186 offset:34816
	ds_read_b128 v[204:207], v186 offset:35840
	ds_read_b128 v[208:211], v186 offset:36864
	ds_read_b128 v[212:215], v186 offset:37888
	ds_read_b128 v[216:219], v186 offset:38912
	ds_read_b128 v[220:223], v186 offset:39936
	global_load_lds_dwordx4 v[230:231], off
	v_lshl_add_u64 v[230:231], s[36:37], 0, v[150:151]
	s_mov_b32 m0, s45
	s_nop 0
	global_load_lds_dwordx4 v[230:231], off
	s_waitcnt vmcnt(8)
	s_waitcnt lgkmcnt(0)
	s_barrier
	s_setprio 1
	s_waitcnt lgkmcnt(0)
	v_mfma_f32_16x16x32_bf16 v[124:127], v[128:131], v[192:195], v[124:127]
	v_mfma_f32_16x16x32_bf16 v[120:123], v[136:139], v[192:195], v[120:123]
	v_mfma_f32_16x16x32_bf16 v[108:111], v[128:131], v[200:203], v[108:111]
	v_mfma_f32_16x16x32_bf16 v[104:107], v[136:139], v[200:203], v[104:107]
	v_mfma_f32_16x16x32_bf16 v[92:95], v[128:131], v[208:211], v[92:95]
	v_mfma_f32_16x16x32_bf16 v[88:91], v[136:139], v[208:211], v[88:91]
	v_mfma_f32_16x16x32_bf16 v[76:79], v[128:131], v[216:219], v[76:79]
	v_mfma_f32_16x16x32_bf16 v[72:75], v[136:139], v[216:219], v[72:75]
	v_mfma_f32_16x16x32_bf16 v[124:127], v[132:135], v[196:199], v[124:127]
	v_mfma_f32_16x16x32_bf16 v[120:123], v[140:143], v[196:199], v[120:123]
	v_mfma_f32_16x16x32_bf16 v[108:111], v[132:135], v[204:207], v[108:111]
	v_mfma_f32_16x16x32_bf16 v[104:107], v[140:143], v[204:207], v[104:107]
	v_mfma_f32_16x16x32_bf16 v[92:95], v[132:135], v[212:215], v[92:95]
	v_mfma_f32_16x16x32_bf16 v[88:91], v[140:143], v[212:215], v[88:91]
	v_mfma_f32_16x16x32_bf16 v[76:79], v[132:135], v[220:223], v[76:79]
	v_mfma_f32_16x16x32_bf16 v[72:75], v[140:143], v[220:223], v[72:75]
	s_setprio 0
	s_setprio 1
	v_mfma_f32_16x16x32_bf16 v[116:119], v[166:169], v[192:195], v[116:119]
	v_mfma_f32_16x16x32_bf16 v[112:115], v[174:177], v[192:195], v[112:115]
	v_mfma_f32_16x16x32_bf16 v[100:103], v[166:169], v[200:203], v[100:103]
	v_mfma_f32_16x16x32_bf16 v[96:99], v[174:177], v[200:203], v[96:99]
	v_mfma_f32_16x16x32_bf16 v[84:87], v[166:169], v[208:211], v[84:87]
	v_mfma_f32_16x16x32_bf16 v[80:83], v[174:177], v[208:211], v[80:83]
	v_mfma_f32_16x16x32_bf16 v[68:71], v[166:169], v[216:219], v[68:71]
	v_mfma_f32_16x16x32_bf16 v[64:67], v[174:177], v[216:219], v[64:67]
	v_mfma_f32_16x16x32_bf16 v[116:119], v[170:173], v[196:199], v[116:119]
	v_mfma_f32_16x16x32_bf16 v[112:115], v[188:191], v[196:199], v[112:115]
	v_mfma_f32_16x16x32_bf16 v[100:103], v[170:173], v[204:207], v[100:103]
	v_mfma_f32_16x16x32_bf16 v[96:99], v[188:191], v[204:207], v[96:99]
	v_mfma_f32_16x16x32_bf16 v[84:87], v[170:173], v[212:215], v[84:87]
	v_mfma_f32_16x16x32_bf16 v[80:83], v[188:191], v[212:215], v[80:83]
	v_mfma_f32_16x16x32_bf16 v[68:71], v[170:173], v[220:223], v[68:71]
	v_mfma_f32_16x16x32_bf16 v[64:67], v[188:191], v[220:223], v[64:67]
	s_setprio 0
	s_barrier
	s_add_i32 s36, s57, s41
	v_lshl_add_u64 v[178:179], v[178:179], 0, s[12:13]
	s_mov_b32 m0, s36
	ds_read_b128 v[192:195], v186 offset:49152
	ds_read_b128 v[196:199], v186 offset:50176
	ds_read_b128 v[200:203], v186 offset:51200
	ds_read_b128 v[204:207], v186 offset:52224
	ds_read_b128 v[208:211], v186 offset:53248
	ds_read_b128 v[212:215], v186 offset:54272
	ds_read_b128 v[216:219], v186 offset:55296
	ds_read_b128 v[220:223], v186 offset:56320
	global_load_lds_dwordx4 v[178:179], off
	s_add_i32 m0, s36, 0x2000
	s_add_u32 s34, s34, 0x40080
	v_lshl_add_u64 v[178:179], v[224:225], 0, s[12:13]
	s_addc_u32 s35, s35, 0
	s_add_i32 s36, s58, s41
	global_load_lds_dwordx4 v[178:179], off
	v_lshl_add_u64 v[178:179], s[34:35], 0, v[148:149]
	s_mov_b32 m0, s36
	s_nop 0
	global_load_lds_dwordx4 v[178:179], off
	v_lshl_add_u64 v[178:179], s[34:35], 0, v[152:153]
	s_add_i32 m0, s36, 0x2000
	s_nop 0
	global_load_lds_dwordx4 v[178:179], off
	v_lshl_add_u64 v[178:179], v[226:227], 0, s[12:13]
	s_mov_b32 m0, s47
	s_nop 0
	global_load_lds_dwordx4 v[178:179], off
	v_lshl_add_u64 v[178:179], v[228:229], 0, s[12:13]
	s_mov_b32 m0, s48
	s_nop 0
	global_load_lds_dwordx4 v[178:179], off
	s_waitcnt vmcnt(8)
	s_waitcnt lgkmcnt(0)
	s_barrier
	s_setprio 1
	s_waitcnt lgkmcnt(0)
	v_mfma_f32_16x16x32_bf16 v[60:63], v[128:131], v[192:195], v[60:63]
	v_mfma_f32_16x16x32_bf16 v[56:59], v[136:139], v[192:195], v[56:59]
	v_mfma_f32_16x16x32_bf16 v[44:47], v[128:131], v[200:203], v[44:47]
	v_mfma_f32_16x16x32_bf16 v[40:43], v[136:139], v[200:203], v[40:43]
	v_mfma_f32_16x16x32_bf16 v[28:31], v[128:131], v[208:211], v[28:31]
	v_mfma_f32_16x16x32_bf16 v[24:27], v[136:139], v[208:211], v[24:27]
	v_mfma_f32_16x16x32_bf16 v[12:15], v[128:131], v[216:219], v[12:15]
	v_mfma_f32_16x16x32_bf16 v[8:11], v[136:139], v[216:219], v[8:11]
	v_mfma_f32_16x16x32_bf16 v[60:63], v[132:135], v[196:199], v[60:63]
	v_mfma_f32_16x16x32_bf16 v[56:59], v[140:143], v[196:199], v[56:59]
	v_mfma_f32_16x16x32_bf16 v[44:47], v[132:135], v[204:207], v[44:47]
	v_mfma_f32_16x16x32_bf16 v[40:43], v[140:143], v[204:207], v[40:43]
	v_mfma_f32_16x16x32_bf16 v[28:31], v[132:135], v[212:215], v[28:31]
	v_mfma_f32_16x16x32_bf16 v[24:27], v[140:143], v[212:215], v[24:27]
	v_mfma_f32_16x16x32_bf16 v[12:15], v[132:135], v[220:223], v[12:15]
	v_mfma_f32_16x16x32_bf16 v[8:11], v[140:143], v[220:223], v[8:11]
	s_setprio 0
	s_setprio 1
	v_mfma_f32_16x16x32_bf16 v[52:55], v[166:169], v[192:195], v[52:55]
	v_mfma_f32_16x16x32_bf16 v[48:51], v[174:177], v[192:195], v[48:51]
	v_mfma_f32_16x16x32_bf16 v[36:39], v[166:169], v[200:203], v[36:39]
	v_mfma_f32_16x16x32_bf16 v[32:35], v[174:177], v[200:203], v[32:35]
	v_mfma_f32_16x16x32_bf16 v[20:23], v[166:169], v[208:211], v[20:23]
	v_mfma_f32_16x16x32_bf16 v[16:19], v[174:177], v[208:211], v[16:19]
	v_mfma_f32_16x16x32_bf16 v[4:7], v[166:169], v[216:219], v[4:7]
	v_mfma_f32_16x16x32_bf16 v[0:3], v[174:177], v[216:219], v[0:3]
	v_mfma_f32_16x16x32_bf16 v[52:55], v[170:173], v[196:199], v[52:55]
	v_mfma_f32_16x16x32_bf16 v[48:51], v[188:191], v[196:199], v[48:51]
	v_mfma_f32_16x16x32_bf16 v[36:39], v[170:173], v[204:207], v[36:39]
	v_mfma_f32_16x16x32_bf16 v[32:35], v[188:191], v[204:207], v[32:35]
	v_mfma_f32_16x16x32_bf16 v[20:23], v[170:173], v[212:215], v[20:23]
	v_mfma_f32_16x16x32_bf16 v[16:19], v[188:191], v[212:215], v[16:19]
	v_mfma_f32_16x16x32_bf16 v[4:7], v[170:173], v[220:223], v[4:7]
	v_mfma_f32_16x16x32_bf16 v[0:3], v[188:191], v[220:223], v[0:3]
	s_setprio 0
	s_barrier
	s_add_i32 s56, s56, 2
	s_add_u32 s30, s30, 0x100
	s_addc_u32 s31, s31, 0
	s_add_u32 s54, s54, 0x100
	s_addc_u32 s55, s55, 0
	s_cmp_gt_u32 s56, 13
	s_cbranch_scc0 .LBB0_1781
	s_and_b64 vcc, exec, s[14:15]
	s_cbranch_vccz .LBB0_1784
	s_barrier

.LBB0_1800:
	s_mov_b32 s98, 1
	s_or_b64 exec, exec, s[26:27]
	s_andn2_b64 vcc, exec, s[2:3]
	s_mov_b64 s[2:3], -1
	s_cbranch_vccnz .LBB0_1777
	s_andn2_b64 vcc, exec, s[8:9]
	s_cbranch_vccnz .LBB0_1776
	s_barrier
	s_branch .LBB0_1776

.LBB0_1858:
	s_mov_b32 s98, 0
	v_readlane_b32 s8, v244, 47
	s_cmp_lt_i32 s8, 9
	v_readlane_b32 s9, v244, 48
	s_cselect_b64 s[2:3], -1, 0
	s_and_b64 s[8:9], s[2:3], s[0:1]
	s_andn2_b64 vcc, exec, s[8:9]
	v_readlane_b32 s10, v244, 49
	v_readlane_b32 s11, v244, 50
	s_cbranch_vccnz .LBB0_1893
	v_readlane_b32 s2, v244, 51
	s_cmpk_lt_i32 s2, 0x300
	s_cselect_b64 s[0:1], -1, 0
	s_cmpk_gt_i32 s2, 0x2ff
	v_readfirstlane_b32 s2, v182
	s_cbranch_scc1 .LBB0_1861
	v_readlane_b32 s5, v244, 51
	s_ashr_i32 s3, s5, 31
	s_lshr_b32 s3, s3, 29
	s_add_i32 s3, s5, s3
	s_ashr_i32 s4, s3, 3
	s_and_b32 s3, s3, -8
	s_sub_i32 s3, s5, s3
	s_cmp_lt_i32 s3, 0
	s_movk_i32 s5, 0x61
	s_cselect_b32 s5, s5, 0x60
	s_mul_i32 s3, s3, s5
	s_add_i32 s3, s3, s4
	s_ashr_i32 s4, s3, 31
	s_lshr_b32 s4, s4, 27
	s_add_i32 s4, s3, s4
	s_ashr_i32 s5, s4, 5
	s_and_b32 s4, s4, 0xffe0
	s_sub_i32 s3, s3, s4
	s_bfe_i32 s4, s3, 0x80000
	s_bfe_u32 s4, s4, 0x3000c
	s_add_i32 s4, s3, s4
	s_bfe_i32 s10, s4, 0x80000
	s_and_b32 s4, s4, 0xf8
	s_sub_i32 s3, s3, s4
	s_lshl_b32 s5, s5, 3
	s_sext_i32_i16 s10, s10
	s_sext_i32_i8 s3, s3
	s_add_i32 s4, s5, s3
	s_ashr_i32 s10, s10, 3

.LBB0_1870:
	ds_read_b128 v[148:151], v157
	ds_read_b128 v[152:155], v157 offset:1024
	ds_read_b128 v[164:167], v157 offset:2048
	ds_read_b128 v[168:171], v157 offset:3072
	ds_read_b128 v[172:175], v158
	ds_read_b128 v[176:179], v158 offset:1024
	ds_read_b128 v[184:187], v158 offset:2048
	ds_read_b128 v[188:191], v158 offset:3072
	s_add_u32 s34, s30, 0xfffc0080
	s_addc_u32 s35, s31, -1
	s_cmp_eq_u32 s55, 12
	s_cselect_b32 s37, s5, s35
	s_cselect_b32 s36, s11, s34
	s_cselect_b32 s35, s23, s54
	s_cselect_b32 s34, s25, s53
	v_lshl_add_u64 v[224:225], s[30:31], 0, v[138:139]
	s_add_i32 m0, s40, 0xc000
	ds_read_b128 v[192:195], v159
	ds_read_b128 v[196:199], v159 offset:1024
	ds_read_b128 v[200:203], v159 offset:2048
	ds_read_b128 v[204:207], v159 offset:3072
	ds_read_b128 v[208:211], v159 offset:4096
	ds_read_b128 v[212:215], v159 offset:5120
	ds_read_b128 v[216:219], v159 offset:6144
	ds_read_b128 v[220:223], v159 offset:7168
	global_load_lds_dwordx4 v[224:225], off
	v_lshl_add_u64 v[224:225], s[30:31], 0, v[140:141]
	s_add_i32 m0, s40, 0xe000
	s_nop 0
	global_load_lds_dwordx4 v[224:225], off
	s_cmp_lg_u32 s98, 0
	s_cbranch_scc1 .Lrelax8_r1
	s_waitcnt vmcnt(8)
	s_branch .Lrelax8_d1

.Lrelax8_d1:
	s_waitcnt lgkmcnt(0)
	s_barrier
	s_setprio 1
	s_waitcnt lgkmcnt(0)
	v_mfma_f32_16x16x32_bf16 v[124:127], v[148:151], v[192:195], v[124:127]
	v_mfma_f32_16x16x32_bf16 v[120:123], v[164:167], v[192:195], v[120:123]
	v_mfma_f32_16x16x32_bf16 v[108:111], v[148:151], v[200:203], v[108:111]
	v_mfma_f32_16x16x32_bf16 v[104:107], v[164:167], v[200:203], v[104:107]
	v_mfma_f32_16x16x32_bf16 v[92:95], v[148:151], v[208:211], v[92:95]
	v_mfma_f32_16x16x32_bf16 v[88:91], v[164:167], v[208:211], v[88:91]
	v_mfma_f32_16x16x32_bf16 v[76:79], v[148:151], v[216:219], v[76:79]
	v_mfma_f32_16x16x32_bf16 v[72:75], v[164:167], v[216:219], v[72:75]
	v_mfma_f32_16x16x32_bf16 v[124:127], v[152:155], v[196:199], v[124:127]
	v_mfma_f32_16x16x32_bf16 v[120:123], v[168:171], v[196:199], v[120:123]
	v_mfma_f32_16x16x32_bf16 v[108:111], v[152:155], v[204:207], v[108:111]
	v_mfma_f32_16x16x32_bf16 v[104:107], v[168:171], v[204:207], v[104:107]
	v_mfma_f32_16x16x32_bf16 v[92:95], v[152:155], v[212:215], v[92:95]
	v_mfma_f32_16x16x32_bf16 v[88:91], v[168:171], v[212:215], v[88:91]
	v_mfma_f32_16x16x32_bf16 v[76:79], v[152:155], v[220:223], v[76:79]
	v_mfma_f32_16x16x32_bf16 v[72:75], v[168:171], v[220:223], v[72:75]
	s_setprio 0
	s_setprio 1
	v_mfma_f32_16x16x32_bf16 v[116:119], v[172:175], v[192:195], v[116:119]
	v_mfma_f32_16x16x32_bf16 v[112:115], v[184:187], v[192:195], v[112:115]
	v_mfma_f32_16x16x32_bf16 v[100:103], v[172:175], v[200:203], v[100:103]
	v_mfma_f32_16x16x32_bf16 v[96:99], v[184:187], v[200:203], v[96:99]
	v_mfma_f32_16x16x32_bf16 v[84:87], v[172:175], v[208:211], v[84:87]
	v_mfma_f32_16x16x32_bf16 v[80:83], v[184:187], v[208:211], v[80:83]
	v_mfma_f32_16x16x32_bf16 v[68:71], v[172:175], v[216:219], v[68:71]
	v_mfma_f32_16x16x32_bf16 v[64:67], v[184:187], v[216:219], v[64:67]
	v_mfma_f32_16x16x32_bf16 v[116:119], v[176:179], v[196:199], v[116:119]
	v_mfma_f32_16x16x32_bf16 v[112:115], v[188:191], v[196:199], v[112:115]
	v_mfma_f32_16x16x32_bf16 v[100:103], v[176:179], v[204:207], v[100:103]
	v_mfma_f32_16x16x32_bf16 v[96:99], v[188:191], v[204:207], v[96:99]
	v_mfma_f32_16x16x32_bf16 v[84:87], v[176:179], v[212:215], v[84:87]
	v_mfma_f32_16x16x32_bf16 v[80:83], v[188:191], v[212:215], v[80:83]
	v_mfma_f32_16x16x32_bf16 v[68:71], v[176:179], v[220:223], v[68:71]
	v_mfma_f32_16x16x32_bf16 v[64:67], v[188:191], v[220:223], v[64:67]
	s_setprio 0
	s_barrier
	s_add_i32 s56, s50, s39
	v_lshl_add_u64 v[224:225], s[34:35], 0, v[130:131]
	s_mov_b32 m0, s56
	ds_read_b128 v[192:195], v159 offset:16384
	ds_read_b128 v[196:199], v159 offset:17408
	ds_read_b128 v[200:203], v159 offset:18432
	ds_read_b128 v[204:207], v159 offset:19456
	ds_read_b128 v[208:211], v159 offset:20480
	ds_read_b128 v[212:215], v159 offset:21504
	ds_read_b128 v[216:219], v159 offset:22528
	ds_read_b128 v[220:223], v159 offset:23552
	global_load_lds_dwordx4 v[224:225], off
	s_add_i32 m0, s56, 0x2000
	s_add_u32 s56, s34, 0x40000
	v_lshl_add_u64 v[226:227], s[34:35], 0, v[134:135]
	s_addc_u32 s57, s35, 0
	s_add_i32 s58, s51, s39
	global_load_lds_dwordx4 v[226:227], off
	v_lshl_add_u64 v[228:229], s[56:57], 0, v[130:131]
	s_mov_b32 m0, s58
	v_lshl_add_u64 v[230:231], s[36:37], 0, v[132:133]
	global_load_lds_dwordx4 v[228:229], off
	v_lshl_add_u64 v[228:229], s[56:57], 0, v[134:135]
	s_add_i32 m0, s58, 0x2000
	s_nop 0
	global_load_lds_dwordx4 v[228:229], off
	v_lshl_add_u64 v[228:229], s[36:37], 0, v[128:129]
	s_mov_b32 m0, s40
	s_nop 0
	global_load_lds_dwordx4 v[228:229], off
	s_mov_b32 m0, s41
	s_nop 0
	global_load_lds_dwordx4 v[230:231], off
	s_cmp_lg_u32 s98, 0
	s_cbranch_scc1 .Lrelax8_r2
	s_waitcnt vmcnt(8)
	s_branch .Lrelax8_d2

.Lrelax8_d2:
	s_mov_b32 s98, 0
	s_waitcnt lgkmcnt(0)
	s_barrier
	s_setprio 1
	s_waitcnt lgkmcnt(0)
	v_mfma_f32_16x16x32_bf16 v[60:63], v[148:151], v[192:195], v[60:63]
	v_mfma_f32_16x16x32_bf16 v[56:59], v[164:167], v[192:195], v[56:59]
	v_mfma_f32_16x16x32_bf16 v[44:47], v[148:151], v[200:203], v[44:47]
	v_mfma_f32_16x16x32_bf16 v[40:43], v[164:167], v[200:203], v[40:43]
	v_mfma_f32_16x16x32_bf16 v[28:31], v[148:151], v[208:211], v[28:31]
	v_mfma_f32_16x16x32_bf16 v[24:27], v[164:167], v[208:211], v[24:27]
	v_mfma_f32_16x16x32_bf16 v[12:15], v[148:151], v[216:219], v[12:15]
	v_mfma_f32_16x16x32_bf16 v[8:11], v[164:167], v[216:219], v[8:11]
	v_mfma_f32_16x16x32_bf16 v[60:63], v[152:155], v[196:199], v[60:63]
	v_mfma_f32_16x16x32_bf16 v[56:59], v[168:171], v[196:199], v[56:59]
	v_mfma_f32_16x16x32_bf16 v[44:47], v[152:155], v[204:207], v[44:47]
	v_mfma_f32_16x16x32_bf16 v[40:43], v[168:171], v[204:207], v[40:43]
	v_mfma_f32_16x16x32_bf16 v[28:31], v[152:155], v[212:215], v[28:31]
	v_mfma_f32_16x16x32_bf16 v[24:27], v[168:171], v[212:215], v[24:27]
	v_mfma_f32_16x16x32_bf16 v[12:15], v[152:155], v[220:223], v[12:15]
	v_mfma_f32_16x16x32_bf16 v[8:11], v[168:171], v[220:223], v[8:11]
	s_setprio 0
	s_setprio 1
	v_mfma_f32_16x16x32_bf16 v[52:55], v[172:175], v[192:195], v[52:55]
	v_mfma_f32_16x16x32_bf16 v[48:51], v[184:187], v[192:195], v[48:51]
	v_mfma_f32_16x16x32_bf16 v[36:39], v[172:175], v[200:203], v[36:39]
	v_mfma_f32_16x16x32_bf16 v[32:35], v[184:187], v[200:203], v[32:35]
	v_mfma_f32_16x16x32_bf16 v[20:23], v[172:175], v[208:211], v[20:23]
	v_mfma_f32_16x16x32_bf16 v[16:19], v[184:187], v[208:211], v[16:19]
	v_mfma_f32_16x16x32_bf16 v[4:7], v[172:175], v[216:219], v[4:7]
	v_mfma_f32_16x16x32_bf16 v[0:3], v[184:187], v[216:219], v[0:3]
	v_mfma_f32_16x16x32_bf16 v[52:55], v[176:179], v[196:199], v[52:55]
	v_mfma_f32_16x16x32_bf16 v[48:51], v[188:191], v[196:199], v[48:51]
	v_mfma_f32_16x16x32_bf16 v[36:39], v[176:179], v[204:207], v[36:39]
	v_mfma_f32_16x16x32_bf16 v[32:35], v[188:191], v[204:207], v[32:35]
	v_mfma_f32_16x16x32_bf16 v[20:23], v[176:179], v[212:215], v[20:23]
	v_mfma_f32_16x16x32_bf16 v[16:19], v[188:191], v[212:215], v[16:19]
	v_mfma_f32_16x16x32_bf16 v[4:7], v[176:179], v[220:223], v[4:7]
	v_mfma_f32_16x16x32_bf16 v[0:3], v[188:191], v[220:223], v[0:3]
	s_setprio 0
	s_barrier
	s_add_i32 s56, 0, 0x18000
	v_add_u32_e32 v163, s56, v156
	s_add_i32 s57, 0, 0x1c000
	ds_read_b128 v[148:151], v163
	ds_read_b128 v[152:155], v163 offset:1024
	ds_read_b128 v[164:167], v163 offset:2048
	ds_read_b128 v[168:171], v163 offset:3072
	v_add_u32_e32 v163, s57, v156
	ds_read_b128 v[172:175], v163
	ds_read_b128 v[176:179], v163 offset:1024
	ds_read_b128 v[184:187], v163 offset:2048
	ds_read_b128 v[188:191], v163 offset:3072
	s_add_u32 s36, s36, 0x40000
	s_addc_u32 s37, s37, 0
	s_mov_b32 m0, s42
	v_lshl_add_u64 v[232:233], s[36:37], 0, v[128:129]
	ds_read_b128 v[192:195], v159 offset:32768
	ds_read_b128 v[196:199], v159 offset:33792
	ds_read_b128 v[200:203], v159 offset:34816
	ds_read_b128 v[204:207], v159 offset:35840
	ds_read_b128 v[208:211], v159 offset:36864
	ds_read_b128 v[212:215], v159 offset:37888
	ds_read_b128 v[216:219], v159 offset:38912
	ds_read_b128 v[220:223], v159 offset:39936
	global_load_lds_dwordx4 v[232:233], off
	v_lshl_add_u64 v[232:233], s[36:37], 0, v[132:133]
	s_mov_b32 m0, s43
	s_nop 0
	global_load_lds_dwordx4 v[232:233], off
	s_waitcnt vmcnt(8)
	s_waitcnt lgkmcnt(0)
	s_barrier
	s_setprio 1
	s_waitcnt lgkmcnt(0)
	v_mfma_f32_16x16x32_bf16 v[124:127], v[148:151], v[192:195], v[124:127]
	v_mfma_f32_16x16x32_bf16 v[120:123], v[164:167], v[192:195], v[120:123]
	v_mfma_f32_16x16x32_bf16 v[108:111], v[148:151], v[200:203], v[108:111]
	v_mfma_f32_16x16x32_bf16 v[104:107], v[164:167], v[200:203], v[104:107]
	v_mfma_f32_16x16x32_bf16 v[92:95], v[148:151], v[208:211], v[92:95]
	v_mfma_f32_16x16x32_bf16 v[88:91], v[164:167], v[208:211], v[88:91]
	v_mfma_f32_16x16x32_bf16 v[76:79], v[148:151], v[216:219], v[76:79]
	v_mfma_f32_16x16x32_bf16 v[72:75], v[164:167], v[216:219], v[72:75]
	v_mfma_f32_16x16x32_bf16 v[124:127], v[152:155], v[196:199], v[124:127]
	v_mfma_f32_16x16x32_bf16 v[120:123], v[168:171], v[196:199], v[120:123]
	v_mfma_f32_16x16x32_bf16 v[108:111], v[152:155], v[204:207], v[108:111]
	v_mfma_f32_16x16x32_bf16 v[104:107], v[168:171], v[204:207], v[104:107]
	v_mfma_f32_16x16x32_bf16 v[92:95], v[152:155], v[212:215], v[92:95]
	v_mfma_f32_16x16x32_bf16 v[88:91], v[168:171], v[212:215], v[88:91]
	v_mfma_f32_16x16x32_bf16 v[76:79], v[152:155], v[220:223], v[76:79]
	v_mfma_f32_16x16x32_bf16 v[72:75], v[168:171], v[220:223], v[72:75]
	s_setprio 0
	s_setprio 1
	v_mfma_f32_16x16x32_bf16 v[116:119], v[172:175], v[192:195], v[116:119]
	v_mfma_f32_16x16x32_bf16 v[112:115], v[184:187], v[192:195], v[112:115]
	v_mfma_f32_16x16x32_bf16 v[100:103], v[172:175], v[200:203], v[100:103]
	v_mfma_f32_16x16x32_bf16 v[96:99], v[184:187], v[200:203], v[96:99]
	v_mfma_f32_16x16x32_bf16 v[84:87], v[172:175], v[208:211], v[84:87]
	v_mfma_f32_16x16x32_bf16 v[80:83], v[184:187], v[208:211], v[80:83]
	v_mfma_f32_16x16x32_bf16 v[68:71], v[172:175], v[216:219], v[68:71]
	v_mfma_f32_16x16x32_bf16 v[64:67], v[184:187], v[216:219], v[64:67]
	v_mfma_f32_16x16x32_bf16 v[116:119], v[176:179], v[196:199], v[116:119]
	v_mfma_f32_16x16x32_bf16 v[112:115], v[188:191], v[196:199], v[112:115]
	v_mfma_f32_16x16x32_bf16 v[100:103], v[176:179], v[204:207], v[100:103]
	v_mfma_f32_16x16x32_bf16 v[96:99], v[188:191], v[204:207], v[96:99]
	v_mfma_f32_16x16x32_bf16 v[84:87], v[176:179], v[212:215], v[84:87]
	v_mfma_f32_16x16x32_bf16 v[80:83], v[188:191], v[212:215], v[80:83]
	v_mfma_f32_16x16x32_bf16 v[68:71], v[176:179], v[220:223], v[68:71]
	v_mfma_f32_16x16x32_bf16 v[64:67], v[188:191], v[220:223], v[64:67]
	s_setprio 0
	s_barrier
	s_add_i32 s36, s56, s39
	v_lshl_add_u64 v[224:225], v[224:225], 0, s[18:19]
	s_mov_b32 m0, s36
	ds_read_b128 v[192:195], v159 offset:49152
	ds_read_b128 v[196:199], v159 offset:50176
	ds_read_b128 v[200:203], v159 offset:51200
	ds_read_b128 v[204:207], v159 offset:52224
	ds_read_b128 v[208:211], v159 offset:53248
	ds_read_b128 v[212:215], v159 offset:54272
	ds_read_b128 v[216:219], v159 offset:55296
	ds_read_b128 v[220:223], v159 offset:56320
	global_load_lds_dwordx4 v[224:225], off
	s_add_i32 m0, s36, 0x2000
	s_add_u32 s34, s34, 0x40080
	v_lshl_add_u64 v[224:225], v[226:227], 0, s[18:19]
	s_addc_u32 s35, s35, 0
	s_add_i32 s36, s57, s39
	global_load_lds_dwordx4 v[224:225], off
	v_lshl_add_u64 v[224:225], s[34:35], 0, v[130:131]
	s_mov_b32 m0, s36
	s_nop 0
	global_load_lds_dwordx4 v[224:225], off
	v_lshl_add_u64 v[224:225], s[34:35], 0, v[134:135]
	s_add_i32 m0, s36, 0x2000
	s_nop 0
	global_load_lds_dwordx4 v[224:225], off
	v_lshl_add_u64 v[224:225], v[228:229], 0, s[18:19]
	s_mov_b32 m0, s45
	s_nop 0
	global_load_lds_dwordx4 v[224:225], off
	v_lshl_add_u64 v[224:225], v[230:231], 0, s[18:19]
	s_mov_b32 m0, s46
	s_nop 0
	global_load_lds_dwordx4 v[224:225], off
	s_waitcnt vmcnt(8)
	s_waitcnt lgkmcnt(0)
	s_barrier
	s_setprio 1
	s_waitcnt lgkmcnt(0)
	v_mfma_f32_16x16x32_bf16 v[60:63], v[148:151], v[192:195], v[60:63]
	v_mfma_f32_16x16x32_bf16 v[56:59], v[164:167], v[192:195], v[56:59]
	v_mfma_f32_16x16x32_bf16 v[44:47], v[148:151], v[200:203], v[44:47]
	v_mfma_f32_16x16x32_bf16 v[40:43], v[164:167], v[200:203], v[40:43]
	v_mfma_f32_16x16x32_bf16 v[28:31], v[148:151], v[208:211], v[28:31]
	v_mfma_f32_16x16x32_bf16 v[24:27], v[164:167], v[208:211], v[24:27]
	v_mfma_f32_16x16x32_bf16 v[12:15], v[148:151], v[216:219], v[12:15]
	v_mfma_f32_16x16x32_bf16 v[8:11], v[164:167], v[216:219], v[8:11]
	v_mfma_f32_16x16x32_bf16 v[60:63], v[152:155], v[196:199], v[60:63]
	v_mfma_f32_16x16x32_bf16 v[56:59], v[168:171], v[196:199], v[56:59]
	v_mfma_f32_16x16x32_bf16 v[44:47], v[152:155], v[204:207], v[44:47]
	v_mfma_f32_16x16x32_bf16 v[40:43], v[168:171], v[204:207], v[40:43]
	v_mfma_f32_16x16x32_bf16 v[28:31], v[152:155], v[212:215], v[28:31]
	v_mfma_f32_16x16x32_bf16 v[24:27], v[168:171], v[212:215], v[24:27]
	v_mfma_f32_16x16x32_bf16 v[12:15], v[152:155], v[220:223], v[12:15]
	v_mfma_f32_16x16x32_bf16 v[8:11], v[168:171], v[220:223], v[8:11]
	s_setprio 0
	s_setprio 1
	v_mfma_f32_16x16x32_bf16 v[52:55], v[172:175], v[192:195], v[52:55]
	v_mfma_f32_16x16x32_bf16 v[48:51], v[184:187], v[192:195], v[48:51]
	v_mfma_f32_16x16x32_bf16 v[36:39], v[172:175], v[200:203], v[36:39]
	v_mfma_f32_16x16x32_bf16 v[32:35], v[184:187], v[200:203], v[32:35]
	v_mfma_f32_16x16x32_bf16 v[20:23], v[172:175], v[208:211], v[20:23]
	v_mfma_f32_16x16x32_bf16 v[16:19], v[184:187], v[208:211], v[16:19]
	v_mfma_f32_16x16x32_bf16 v[4:7], v[172:175], v[216:219], v[4:7]
	v_mfma_f32_16x16x32_bf16 v[0:3], v[184:187], v[216:219], v[0:3]
	v_mfma_f32_16x16x32_bf16 v[52:55], v[176:179], v[196:199], v[52:55]
	v_mfma_f32_16x16x32_bf16 v[48:51], v[188:191], v[196:199], v[48:51]
	v_mfma_f32_16x16x32_bf16 v[36:39], v[176:179], v[204:207], v[36:39]
	v_mfma_f32_16x16x32_bf16 v[32:35], v[188:191], v[204:207], v[32:35]
	v_mfma_f32_16x16x32_bf16 v[20:23], v[176:179], v[212:215], v[20:23]
	v_mfma_f32_16x16x32_bf16 v[16:19], v[188:191], v[212:215], v[16:19]
	v_mfma_f32_16x16x32_bf16 v[4:7], v[176:179], v[220:223], v[4:7]
	v_mfma_f32_16x16x32_bf16 v[0:3], v[188:191], v[220:223], v[0:3]
	s_setprio 0
	s_barrier
	s_add_i32 s55, s55, 2
	s_add_u32 s30, s30, 0x100
	s_addc_u32 s31, s31, 0
	s_add_u32 s53, s53, 0x100
	s_addc_u32 s54, s54, 0
	s_cmp_gt_u32 s55, 13
	s_cbranch_scc0 .LBB0_1870
	s_and_b64 vcc, exec, s[20:21]
	s_cbranch_vccz .LBB0_1873
	s_barrier

.LBB0_1889:
	s_mov_b32 s98, 1
	s_or_b64 exec, exec, s[4:5]
	s_andn2_b64 vcc, exec, s[2:3]
	s_mov_b64 s[2:3], -1
	s_cbranch_vccnz .LBB0_1866
	s_andn2_b64 vcc, exec, s[12:13]
	s_cbranch_vccnz .LBB0_1865
	s_barrier
	s_branch .LBB0_1865

.LBB0_2010:
	s_mov_b32 s98, 0
	v_readlane_b32 s4, v244, 47
	s_cmp_lt_i32 s4, 11
	v_readlane_b32 s5, v244, 48
	s_cselect_b64 s[2:3], -1, 0
	s_and_b64 s[4:5], s[2:3], s[0:1]
	s_andn2_b64 vcc, exec, s[4:5]
	v_readlane_b32 s6, v244, 49
	v_readlane_b32 s7, v244, 50
	s_cbranch_vccnz .LBB0_2045
	v_readlane_b32 s2, v244, 51
	s_cmpk_lt_i32 s2, 0x300
	s_cselect_b64 s[0:1], -1, 0
	s_cmpk_gt_i32 s2, 0x2ff
	v_readfirstlane_b32 s2, v182
	s_cbranch_scc1 .LBB0_2013
	v_readlane_b32 s7, v244, 51
	s_ashr_i32 s3, s7, 31
	s_lshr_b32 s3, s3, 29
	s_add_i32 s3, s7, s3
	s_ashr_i32 s6, s3, 3
	s_and_b32 s3, s3, -8
	s_sub_i32 s3, s7, s3
	s_cmp_lt_i32 s3, 0
	s_movk_i32 s7, 0x61
	s_cselect_b32 s7, s7, 0x60
	s_mul_i32 s3, s3, s7
	s_add_i32 s3, s3, s6
	s_ashr_i32 s6, s3, 31
	s_lshr_b32 s6, s6, 27
	s_add_i32 s6, s3, s6
	s_ashr_i32 s7, s6, 5
	s_and_b32 s6, s6, 0xffe0
	s_sub_i32 s3, s3, s6
	s_bfe_i32 s6, s3, 0x80000
	s_bfe_u32 s6, s6, 0x3000c
	s_add_i32 s6, s3, s6
	s_bfe_i32 s8, s6, 0x80000
	s_and_b32 s6, s6, 0xf8
	s_sub_i32 s3, s3, s6
	s_lshl_b32 s7, s7, 3
	s_sext_i32_i16 s8, s8
	s_sext_i32_i8 s3, s3
	s_add_i32 s28, s7, s3
	s_ashr_i32 s26, s8, 3

.LBB0_2022:
	ds_read_b128 v[128:131], v178
	ds_read_b128 v[132:135], v178 offset:1024
	ds_read_b128 v[136:139], v178 offset:2048
	ds_read_b128 v[140:143], v178 offset:3072
	ds_read_b128 v[164:167], v179
	ds_read_b128 v[168:171], v179 offset:1024
	ds_read_b128 v[172:175], v179 offset:2048
	ds_read_b128 v[184:187], v179 offset:3072
	s_add_u32 s34, s30, 0xfffc0080
	s_addc_u32 s35, s31, -1
	s_cmp_eq_u32 s56, 12
	s_cselect_b32 s37, s21, s35
	s_cselect_b32 s36, s27, s34
	s_cselect_b32 s35, s19, s55
	s_cselect_b32 s34, s29, s54
	v_lshl_add_u64 v[220:221], s[30:31], 0, v[156:157]
	s_add_i32 m0, s42, 0xc000
	ds_read_b128 v[188:191], v180
	ds_read_b128 v[192:195], v180 offset:1024
	ds_read_b128 v[196:199], v180 offset:2048
	ds_read_b128 v[200:203], v180 offset:3072
	ds_read_b128 v[204:207], v180 offset:4096
	ds_read_b128 v[208:211], v180 offset:5120
	ds_read_b128 v[212:215], v180 offset:6144
	ds_read_b128 v[216:219], v180 offset:7168
	global_load_lds_dwordx4 v[220:221], off
	v_lshl_add_u64 v[220:221], s[30:31], 0, v[158:159]
	s_add_i32 m0, s42, 0xe000
	s_nop 0
	global_load_lds_dwordx4 v[220:221], off
	s_cmp_lg_u32 s98, 0
	s_cbranch_scc1 .Lrelax10_r1
	s_waitcnt vmcnt(8)
	s_branch .Lrelax10_d1

.Lrelax10_d1:
	s_waitcnt lgkmcnt(0)
	s_barrier
	s_setprio 1
	s_waitcnt lgkmcnt(0)
	v_mfma_f32_16x16x32_bf16 v[124:127], v[128:131], v[188:191], v[124:127]
	v_mfma_f32_16x16x32_bf16 v[120:123], v[136:139], v[188:191], v[120:123]
	v_mfma_f32_16x16x32_bf16 v[108:111], v[128:131], v[196:199], v[108:111]
	v_mfma_f32_16x16x32_bf16 v[104:107], v[136:139], v[196:199], v[104:107]
	v_mfma_f32_16x16x32_bf16 v[92:95], v[128:131], v[204:207], v[92:95]
	v_mfma_f32_16x16x32_bf16 v[88:91], v[136:139], v[204:207], v[88:91]
	v_mfma_f32_16x16x32_bf16 v[76:79], v[128:131], v[212:215], v[76:79]
	v_mfma_f32_16x16x32_bf16 v[72:75], v[136:139], v[212:215], v[72:75]
	v_mfma_f32_16x16x32_bf16 v[124:127], v[132:135], v[192:195], v[124:127]
	v_mfma_f32_16x16x32_bf16 v[120:123], v[140:143], v[192:195], v[120:123]
	v_mfma_f32_16x16x32_bf16 v[108:111], v[132:135], v[200:203], v[108:111]
	v_mfma_f32_16x16x32_bf16 v[104:107], v[140:143], v[200:203], v[104:107]
	v_mfma_f32_16x16x32_bf16 v[92:95], v[132:135], v[208:211], v[92:95]
	v_mfma_f32_16x16x32_bf16 v[88:91], v[140:143], v[208:211], v[88:91]
	v_mfma_f32_16x16x32_bf16 v[76:79], v[132:135], v[216:219], v[76:79]
	v_mfma_f32_16x16x32_bf16 v[72:75], v[140:143], v[216:219], v[72:75]
	s_setprio 0
	s_setprio 1
	v_mfma_f32_16x16x32_bf16 v[116:119], v[164:167], v[188:191], v[116:119]
	v_mfma_f32_16x16x32_bf16 v[112:115], v[172:175], v[188:191], v[112:115]
	v_mfma_f32_16x16x32_bf16 v[100:103], v[164:167], v[196:199], v[100:103]
	v_mfma_f32_16x16x32_bf16 v[96:99], v[172:175], v[196:199], v[96:99]
	v_mfma_f32_16x16x32_bf16 v[84:87], v[164:167], v[204:207], v[84:87]
	v_mfma_f32_16x16x32_bf16 v[80:83], v[172:175], v[204:207], v[80:83]
	v_mfma_f32_16x16x32_bf16 v[68:71], v[164:167], v[212:215], v[68:71]
	v_mfma_f32_16x16x32_bf16 v[64:67], v[172:175], v[212:215], v[64:67]
	v_mfma_f32_16x16x32_bf16 v[116:119], v[168:171], v[192:195], v[116:119]
	v_mfma_f32_16x16x32_bf16 v[112:115], v[184:187], v[192:195], v[112:115]
	v_mfma_f32_16x16x32_bf16 v[100:103], v[168:171], v[200:203], v[100:103]
	v_mfma_f32_16x16x32_bf16 v[96:99], v[184:187], v[200:203], v[96:99]
	v_mfma_f32_16x16x32_bf16 v[84:87], v[168:171], v[208:211], v[84:87]
	v_mfma_f32_16x16x32_bf16 v[80:83], v[184:187], v[208:211], v[80:83]
	v_mfma_f32_16x16x32_bf16 v[68:71], v[168:171], v[216:219], v[68:71]
	v_mfma_f32_16x16x32_bf16 v[64:67], v[184:187], v[216:219], v[64:67]
	s_setprio 0
	s_barrier
	s_add_i32 s57, s52, s41
	v_lshl_add_u64 v[220:221], s[34:35], 0, v[146:147]
	s_mov_b32 m0, s57
	ds_read_b128 v[188:191], v180 offset:16384
	ds_read_b128 v[192:195], v180 offset:17408
	ds_read_b128 v[196:199], v180 offset:18432
	ds_read_b128 v[200:203], v180 offset:19456
	ds_read_b128 v[204:207], v180 offset:20480
	ds_read_b128 v[208:211], v180 offset:21504
	ds_read_b128 v[212:215], v180 offset:22528
	ds_read_b128 v[216:219], v180 offset:23552
	global_load_lds_dwordx4 v[220:221], off
	s_add_i32 m0, s57, 0x2000
	s_add_u32 s58, s34, 0x40000
	v_lshl_add_u64 v[222:223], s[34:35], 0, v[150:151]
	s_addc_u32 s59, s35, 0
	s_add_i32 s57, s53, s41
	global_load_lds_dwordx4 v[222:223], off
	v_lshl_add_u64 v[224:225], s[58:59], 0, v[146:147]
	s_mov_b32 m0, s57
	v_lshl_add_u64 v[226:227], s[36:37], 0, v[148:149]
	global_load_lds_dwordx4 v[224:225], off
	v_lshl_add_u64 v[224:225], s[58:59], 0, v[150:151]
	s_add_i32 m0, s57, 0x2000
	s_nop 0
	global_load_lds_dwordx4 v[224:225], off
	v_lshl_add_u64 v[224:225], s[36:37], 0, v[144:145]
	s_mov_b32 m0, s42
	s_nop 0
	global_load_lds_dwordx4 v[224:225], off
	s_mov_b32 m0, s43
	s_nop 0
	global_load_lds_dwordx4 v[226:227], off
	s_cmp_lg_u32 s98, 0
	s_cbranch_scc1 .Lrelax10_r2
	s_waitcnt vmcnt(8)
	s_branch .Lrelax10_d2

.Lrelax10_d2:
	s_mov_b32 s98, 0
	s_waitcnt lgkmcnt(0)
	s_barrier
	s_setprio 1
	s_waitcnt lgkmcnt(0)
	v_mfma_f32_16x16x32_bf16 v[60:63], v[128:131], v[188:191], v[60:63]
	v_mfma_f32_16x16x32_bf16 v[56:59], v[136:139], v[188:191], v[56:59]
	v_mfma_f32_16x16x32_bf16 v[44:47], v[128:131], v[196:199], v[44:47]
	v_mfma_f32_16x16x32_bf16 v[40:43], v[136:139], v[196:199], v[40:43]
	v_mfma_f32_16x16x32_bf16 v[28:31], v[128:131], v[204:207], v[28:31]
	v_mfma_f32_16x16x32_bf16 v[24:27], v[136:139], v[204:207], v[24:27]
	v_mfma_f32_16x16x32_bf16 v[12:15], v[128:131], v[212:215], v[12:15]
	v_mfma_f32_16x16x32_bf16 v[8:11], v[136:139], v[212:215], v[8:11]
	v_mfma_f32_16x16x32_bf16 v[60:63], v[132:135], v[192:195], v[60:63]
	v_mfma_f32_16x16x32_bf16 v[56:59], v[140:143], v[192:195], v[56:59]
	v_mfma_f32_16x16x32_bf16 v[44:47], v[132:135], v[200:203], v[44:47]
	v_mfma_f32_16x16x32_bf16 v[40:43], v[140:143], v[200:203], v[40:43]
	v_mfma_f32_16x16x32_bf16 v[28:31], v[132:135], v[208:211], v[28:31]
	v_mfma_f32_16x16x32_bf16 v[24:27], v[140:143], v[208:211], v[24:27]
	v_mfma_f32_16x16x32_bf16 v[12:15], v[132:135], v[216:219], v[12:15]
	v_mfma_f32_16x16x32_bf16 v[8:11], v[140:143], v[216:219], v[8:11]
	s_setprio 0
	s_setprio 1
	v_mfma_f32_16x16x32_bf16 v[52:55], v[164:167], v[188:191], v[52:55]
	v_mfma_f32_16x16x32_bf16 v[48:51], v[172:175], v[188:191], v[48:51]
	v_mfma_f32_16x16x32_bf16 v[36:39], v[164:167], v[196:199], v[36:39]
	v_mfma_f32_16x16x32_bf16 v[32:35], v[172:175], v[196:199], v[32:35]
	v_mfma_f32_16x16x32_bf16 v[20:23], v[164:167], v[204:207], v[20:23]
	v_mfma_f32_16x16x32_bf16 v[16:19], v[172:175], v[204:207], v[16:19]
	v_mfma_f32_16x16x32_bf16 v[4:7], v[164:167], v[212:215], v[4:7]
	v_mfma_f32_16x16x32_bf16 v[0:3], v[172:175], v[212:215], v[0:3]
	v_mfma_f32_16x16x32_bf16 v[52:55], v[168:171], v[192:195], v[52:55]
	v_mfma_f32_16x16x32_bf16 v[48:51], v[184:187], v[192:195], v[48:51]
	v_mfma_f32_16x16x32_bf16 v[36:39], v[168:171], v[200:203], v[36:39]
	v_mfma_f32_16x16x32_bf16 v[32:35], v[184:187], v[200:203], v[32:35]
	v_mfma_f32_16x16x32_bf16 v[20:23], v[168:171], v[208:211], v[20:23]
	v_mfma_f32_16x16x32_bf16 v[16:19], v[184:187], v[208:211], v[16:19]
	v_mfma_f32_16x16x32_bf16 v[4:7], v[168:171], v[216:219], v[4:7]
	v_mfma_f32_16x16x32_bf16 v[0:3], v[184:187], v[216:219], v[0:3]
	s_setprio 0
	s_barrier
	s_add_i32 s57, 0, 0x18000
	s_add_i32 s58, 0, 0x1c000
	v_add_u32_e32 v140, s57, v177
	v_add_u32_e32 v183, s58, v177
	ds_read_b128 v[128:131], v140
	ds_read_b128 v[132:135], v140 offset:1024
	ds_read_b128 v[136:139], v140 offset:2048
	ds_read_b128 v[140:143], v140 offset:3072
	ds_read_b128 v[164:167], v183
	ds_read_b128 v[168:171], v183 offset:1024
	ds_read_b128 v[172:175], v183 offset:2048
	ds_read_b128 v[184:187], v183 offset:3072
	s_add_u32 s36, s36, 0x40000
	s_addc_u32 s37, s37, 0
	s_mov_b32 m0, s44
	v_lshl_add_u64 v[228:229], s[36:37], 0, v[144:145]
	ds_read_b128 v[188:191], v180 offset:32768
	ds_read_b128 v[192:195], v180 offset:33792
	ds_read_b128 v[196:199], v180 offset:34816
	ds_read_b128 v[200:203], v180 offset:35840
	ds_read_b128 v[204:207], v180 offset:36864
	ds_read_b128 v[208:211], v180 offset:37888
	ds_read_b128 v[212:215], v180 offset:38912
	ds_read_b128 v[216:219], v180 offset:39936
	global_load_lds_dwordx4 v[228:229], off
	v_lshl_add_u64 v[228:229], s[36:37], 0, v[148:149]
	s_mov_b32 m0, s45
	s_nop 0
	global_load_lds_dwordx4 v[228:229], off
	s_waitcnt vmcnt(8)
	s_waitcnt lgkmcnt(0)
	s_barrier
	s_setprio 1
	s_waitcnt lgkmcnt(0)
	v_mfma_f32_16x16x32_bf16 v[124:127], v[128:131], v[188:191], v[124:127]
	v_mfma_f32_16x16x32_bf16 v[120:123], v[136:139], v[188:191], v[120:123]
	v_mfma_f32_16x16x32_bf16 v[108:111], v[128:131], v[196:199], v[108:111]
	v_mfma_f32_16x16x32_bf16 v[104:107], v[136:139], v[196:199], v[104:107]
	v_mfma_f32_16x16x32_bf16 v[92:95], v[128:131], v[204:207], v[92:95]
	v_mfma_f32_16x16x32_bf16 v[88:91], v[136:139], v[204:207], v[88:91]
	v_mfma_f32_16x16x32_bf16 v[76:79], v[128:131], v[212:215], v[76:79]
	v_mfma_f32_16x16x32_bf16 v[72:75], v[136:139], v[212:215], v[72:75]
	v_mfma_f32_16x16x32_bf16 v[124:127], v[132:135], v[192:195], v[124:127]
	v_mfma_f32_16x16x32_bf16 v[120:123], v[140:143], v[192:195], v[120:123]
	v_mfma_f32_16x16x32_bf16 v[108:111], v[132:135], v[200:203], v[108:111]
	v_mfma_f32_16x16x32_bf16 v[104:107], v[140:143], v[200:203], v[104:107]
	v_mfma_f32_16x16x32_bf16 v[92:95], v[132:135], v[208:211], v[92:95]
	v_mfma_f32_16x16x32_bf16 v[88:91], v[140:143], v[208:211], v[88:91]
	v_mfma_f32_16x16x32_bf16 v[76:79], v[132:135], v[216:219], v[76:79]
	v_mfma_f32_16x16x32_bf16 v[72:75], v[140:143], v[216:219], v[72:75]
	s_setprio 0
	s_setprio 1
	v_mfma_f32_16x16x32_bf16 v[116:119], v[164:167], v[188:191], v[116:119]
	v_mfma_f32_16x16x32_bf16 v[112:115], v[172:175], v[188:191], v[112:115]
	v_mfma_f32_16x16x32_bf16 v[100:103], v[164:167], v[196:199], v[100:103]
	v_mfma_f32_16x16x32_bf16 v[96:99], v[172:175], v[196:199], v[96:99]
	v_mfma_f32_16x16x32_bf16 v[84:87], v[164:167], v[204:207], v[84:87]
	v_mfma_f32_16x16x32_bf16 v[80:83], v[172:175], v[204:207], v[80:83]
	v_mfma_f32_16x16x32_bf16 v[68:71], v[164:167], v[212:215], v[68:71]
	v_mfma_f32_16x16x32_bf16 v[64:67], v[172:175], v[212:215], v[64:67]
	v_mfma_f32_16x16x32_bf16 v[116:119], v[168:171], v[192:195], v[116:119]
	v_mfma_f32_16x16x32_bf16 v[112:115], v[184:187], v[192:195], v[112:115]
	v_mfma_f32_16x16x32_bf16 v[100:103], v[168:171], v[200:203], v[100:103]
	v_mfma_f32_16x16x32_bf16 v[96:99], v[184:187], v[200:203], v[96:99]
	v_mfma_f32_16x16x32_bf16 v[84:87], v[168:171], v[208:211], v[84:87]
	v_mfma_f32_16x16x32_bf16 v[80:83], v[184:187], v[208:211], v[80:83]
	v_mfma_f32_16x16x32_bf16 v[68:71], v[168:171], v[216:219], v[68:71]
	v_mfma_f32_16x16x32_bf16 v[64:67], v[184:187], v[216:219], v[64:67]
	s_setprio 0
	s_barrier
	s_add_i32 s36, s57, s41
	v_lshl_add_u64 v[220:221], v[220:221], 0, s[12:13]
	s_mov_b32 m0, s36
	ds_read_b128 v[188:191], v180 offset:49152
	ds_read_b128 v[192:195], v180 offset:50176
	ds_read_b128 v[196:199], v180 offset:51200
	ds_read_b128 v[200:203], v180 offset:52224
	ds_read_b128 v[204:207], v180 offset:53248
	ds_read_b128 v[208:211], v180 offset:54272
	ds_read_b128 v[212:215], v180 offset:55296
	ds_read_b128 v[216:219], v180 offset:56320
	global_load_lds_dwordx4 v[220:221], off
	s_add_i32 m0, s36, 0x2000
	s_add_u32 s34, s34, 0x40080
	v_lshl_add_u64 v[220:221], v[222:223], 0, s[12:13]
	s_addc_u32 s35, s35, 0
	s_add_i32 s36, s58, s41
	global_load_lds_dwordx4 v[220:221], off
	v_lshl_add_u64 v[220:221], s[34:35], 0, v[146:147]
	s_mov_b32 m0, s36
	s_nop 0
	global_load_lds_dwordx4 v[220:221], off
	v_lshl_add_u64 v[220:221], s[34:35], 0, v[150:151]
	s_add_i32 m0, s36, 0x2000
	s_nop 0
	global_load_lds_dwordx4 v[220:221], off
	v_lshl_add_u64 v[220:221], v[224:225], 0, s[12:13]
	s_mov_b32 m0, s47
	s_nop 0
	global_load_lds_dwordx4 v[220:221], off
	v_lshl_add_u64 v[220:221], v[226:227], 0, s[12:13]
	s_mov_b32 m0, s48
	s_nop 0
	global_load_lds_dwordx4 v[220:221], off
	s_waitcnt vmcnt(8)
	s_waitcnt lgkmcnt(0)
	s_barrier
	s_setprio 1
	s_waitcnt lgkmcnt(0)
	v_mfma_f32_16x16x32_bf16 v[60:63], v[128:131], v[188:191], v[60:63]
	v_mfma_f32_16x16x32_bf16 v[56:59], v[136:139], v[188:191], v[56:59]
	v_mfma_f32_16x16x32_bf16 v[44:47], v[128:131], v[196:199], v[44:47]
	v_mfma_f32_16x16x32_bf16 v[40:43], v[136:139], v[196:199], v[40:43]
	v_mfma_f32_16x16x32_bf16 v[28:31], v[128:131], v[204:207], v[28:31]
	v_mfma_f32_16x16x32_bf16 v[24:27], v[136:139], v[204:207], v[24:27]
	v_mfma_f32_16x16x32_bf16 v[12:15], v[128:131], v[212:215], v[12:15]
	v_mfma_f32_16x16x32_bf16 v[8:11], v[136:139], v[212:215], v[8:11]
	v_mfma_f32_16x16x32_bf16 v[60:63], v[132:135], v[192:195], v[60:63]
	v_mfma_f32_16x16x32_bf16 v[56:59], v[140:143], v[192:195], v[56:59]
	v_mfma_f32_16x16x32_bf16 v[44:47], v[132:135], v[200:203], v[44:47]
	v_mfma_f32_16x16x32_bf16 v[40:43], v[140:143], v[200:203], v[40:43]
	v_mfma_f32_16x16x32_bf16 v[28:31], v[132:135], v[208:211], v[28:31]
	v_mfma_f32_16x16x32_bf16 v[24:27], v[140:143], v[208:211], v[24:27]
	v_mfma_f32_16x16x32_bf16 v[12:15], v[132:135], v[216:219], v[12:15]
	v_mfma_f32_16x16x32_bf16 v[8:11], v[140:143], v[216:219], v[8:11]
	s_setprio 0
	s_setprio 1
	v_mfma_f32_16x16x32_bf16 v[52:55], v[164:167], v[188:191], v[52:55]
	v_mfma_f32_16x16x32_bf16 v[48:51], v[172:175], v[188:191], v[48:51]
	v_mfma_f32_16x16x32_bf16 v[36:39], v[164:167], v[196:199], v[36:39]
	v_mfma_f32_16x16x32_bf16 v[32:35], v[172:175], v[196:199], v[32:35]
	v_mfma_f32_16x16x32_bf16 v[20:23], v[164:167], v[204:207], v[20:23]
	v_mfma_f32_16x16x32_bf16 v[16:19], v[172:175], v[204:207], v[16:19]
	v_mfma_f32_16x16x32_bf16 v[4:7], v[164:167], v[212:215], v[4:7]
	v_mfma_f32_16x16x32_bf16 v[0:3], v[172:175], v[212:215], v[0:3]
	v_mfma_f32_16x16x32_bf16 v[52:55], v[168:171], v[192:195], v[52:55]
	v_mfma_f32_16x16x32_bf16 v[48:51], v[184:187], v[192:195], v[48:51]
	v_mfma_f32_16x16x32_bf16 v[36:39], v[168:171], v[200:203], v[36:39]
	v_mfma_f32_16x16x32_bf16 v[32:35], v[184:187], v[200:203], v[32:35]
	v_mfma_f32_16x16x32_bf16 v[20:23], v[168:171], v[208:211], v[20:23]
	v_mfma_f32_16x16x32_bf16 v[16:19], v[184:187], v[208:211], v[16:19]
	v_mfma_f32_16x16x32_bf16 v[4:7], v[168:171], v[216:219], v[4:7]
	v_mfma_f32_16x16x32_bf16 v[0:3], v[184:187], v[216:219], v[0:3]
	s_setprio 0
	s_barrier
	s_add_i32 s56, s56, 2
	s_add_u32 s30, s30, 0x100
	s_addc_u32 s31, s31, 0
	s_add_u32 s54, s54, 0x100
	s_addc_u32 s55, s55, 0
	s_cmp_gt_u32 s56, 13
	s_cbranch_scc0 .LBB0_2022
	s_and_b64 vcc, exec, s[14:15]
	s_cbranch_vccz .LBB0_2025
	s_barrier

.LBB0_2041:
	s_mov_b32 s98, 1
	s_or_b64 exec, exec, s[26:27]
	s_andn2_b64 vcc, exec, s[2:3]
	s_mov_b64 s[2:3], -1
	s_cbranch_vccnz .LBB0_2018
	s_andn2_b64 vcc, exec, s[6:7]
	s_cbranch_vccnz .LBB0_2017
	s_barrier
	s_branch .LBB0_2017
